# sample retention units: group-norm gain and gate loads issued at the item start so the epilogue no longer waits for the state-row stores to drain
# speedup vs baseline: 1.0063x; 1.0012x over previous
; __device__ void sample_ret_unit(const Params& p, int l, int unit, LAS unsigned char* lds, const int tid_in) {
;     const int tid = launder(tid_in);
;     const int wid = tid >> 6, lane = tid & 63;
;     const int b = unit >> 3, h = unit & 7, r0 = b * 8;
;     const float lg = lg2gamma(h);
;     LAS float* sq = (LAS float*)lds; LAS float* sk = sq + 2048; LAS float* sv = sk + 2048; LAS float* sqT = sv + 2048; LAS float* skdT = sqT + 2048; LAS float* sc = skdT + 2048; LAS float* red = (LAS float*)(lds + 49152);
;     const bf16_t* zb = (const bf16_t*)(pws(p) + OFF_ZB);
;     { const int i = tid >> 6, d = (tid & 63) * 4; const bf16_t* zr = zb + (size_t)(r0 + i) * ZW + h * 256 + d;
;         const u32x2 a = *(const u32x2*)(zr + ZC_Q), kk = *(const u32x2*)(zr + ZC_K), vv = *(const u32x2*)(zr + ZC_V);
;         const float qf[4] = {bf_lo(a.x), bf_hi(a.x), bf_lo(a.y), bf_hi(a.y)}, kf[4] = {bf_lo(kk.x), bf_hi(kk.x), bf_lo(kk.y), bf_hi(kk.y)};
;         const float dk = exp2f(lg * (float)(7 - i));
;         *(LAS f32x4*)(sq + i * 256 + d) = (f32x4){qf[0], qf[1], qf[2], qf[3]};
;         *(LAS f32x4*)(sk + i * 256 + d) = (f32x4){kf[0], kf[1], kf[2], kf[3]};
;         *(LAS f32x4*)(sv + i * 256 + d) = (f32x4){bf_lo(vv.x), bf_hi(vv.x), bf_lo(vv.y), bf_hi(vv.y)};
; #pragma unroll
;         for (int j = 0; j < 4; ++j) { sqT[(d + j) * 8 + i] = qf[j]; skdT[(d + j) * 8 + i] = kf[j] * dk; } }
;     __syncthreads();
;     { const int i = wid; const f32x4 qv = *(const LAS f32x4*)(sq + i * 256 + lane * 4);
;         for (int j = 0; j < 8; ++j) { const f32x4 kv = *(const LAS f32x4*)(sk + j * 256 + lane * 4);
;             float s = wave_sum(qv[0] * kv[0] + qv[1] * kv[1] + qv[2] * kv[2] + qv[3] * kv[3]);
;             if (lane == 0) sc[i * 8 + j] = j <= i ? s * exp2f(lg * (float)(i - j)) : 0.f; } }
;     const int e4 = lane * 4;
;     f32x4 vv[8], oacc[8];
; #pragma unroll
;     for (int j = 0; j < 8; ++j) { vv[j] = *(const LAS f32x4*)(sv + j * 256 + e4); oacc[j] = (f32x4){0.f, 0.f, 0.f, 0.f}; }
;     const float g8 = exp2f(lg * 8.0f);
;     const size_t sbase = (((size_t)l * 128 + b) * 8 + h) * 65536;
;     const float* Sin = p.state_ret + sbase; float* Sout = pout(p) + O_RS + sbase;
;     f32x4 S4[8], N4[8];
; #pragma unroll
;     for (int u = 0; u < 8; ++u) S4[u] = __builtin_nontemporal_load((const f32x4*)(Sin + (size_t)(wid * 32 + u) * 256 + e4));
.LBB0_522:
	s_and_b64 vcc, exec, s[0:1]
	s_cbranch_vccz .LBB0_544
	v_mov_b32_e32 v0, v244
	s_and_b32 s9, s38, 7
	v_ashrrev_i32_e32 v138, 6, v0
	v_and_b32_e32 v139, 63, v0
	v_cvt_f32_ubyte0_e32 v0, s9
	v_sub_f32_e32 v0, 0xc0a00000, v0
	v_cmp_gt_f32_e32 vcc, s75, v0
	s_and_b32 s8, s38, -8
	s_and_b64 s[0:1], vcc, exec
	s_waitcnt vmcnt(0)
	v_cndmask_b32_e32 v2, 0, v237, vcc
	v_add_f32_e32 v0, v0, v2
	v_exp_f32_e32 v0, v0
	s_cselect_b32 s0, 0xffffffc0, 0
	s_lshl_b32 s90, s9, 9
	v_ldexp_f32 v10, v0, s0
	v_sub_f32_e32 v0, 1.0, v10
	v_add_f32_e32 v2, -1.0, v0
	v_sub_f32_e32 v3, v2, v0
	v_add_f32_e32 v3, 1.0, v3
	v_sub_f32_e64 v2, -v10, v2
	v_add_f32_e32 v4, v2, v3
	v_frexp_mant_f32_e32 v5, v0
	v_cvt_f64_f32_e32 v[2:3], v0
	s_mov_b32 s0, 0x3f2aaaab
	v_frexp_exp_i32_f64_e32 v2, v[2:3]
	v_cmp_gt_f32_e32 vcc, s0, v5
	v_readlane_b32 s0, v253, 19
	v_readlane_b32 s1, v253, 20
	v_subbrev_co_u32_e32 v11, vcc, 0, v2, vcc
	v_sub_u32_e32 v2, 0, v11
	v_ldexp_f32 v0, v0, v2
	v_add_f32_e32 v3, -1.0, v0
	v_add_f32_e32 v6, 1.0, v0
	v_ldexp_f32 v2, v4, v2
	v_add_f32_e32 v4, 1.0, v3
	v_add_f32_e32 v7, -1.0, v6
	v_sub_f32_e32 v4, v0, v4
	v_sub_f32_e32 v0, v0, v7
	v_add_f32_e32 v0, v2, v0
	v_add_f32_e32 v12, v6, v0
	v_rcp_f32_e32 v14, v12
	v_add_f32_e32 v4, v2, v4
	v_add_f32_e32 v5, v3, v4
	v_sub_f32_e32 v2, v12, v6
	v_mul_f32_e32 v15, v5, v14
	v_sub_f32_e32 v13, v0, v2
	v_mul_f32_e32 v0, v12, v15
	v_fma_f32 v9, v15, v12, -v0
	v_fmac_f32_e32 v9, v15, v13
	v_add_f32_e32 v2, v0, v9
	v_sub_f32_e32 v17, v5, v2
	v_sub_f32_e32 v3, v5, v3
	v_sub_f32_e32 v16, v2, v0
	v_sub_f32_e32 v0, v5, v17
	v_sub_f32_e32 v8, v4, v3
	v_sub_f32_e32 v18, v0, v2
	v_add_u32_e32 v0, s8, v138
	v_mov_b64_e32 v[2:3], s[0:1]
	v_mad_i64_i32 v[140:141], s[0:1], v0, s74, v[2:3]
	v_lshl_add_u64 v[2:3], v[140:141], 0, s[90:91]
	v_lshlrev_b32_e32 v0, 3, v139
	v_lshl_add_u64 v[2:3], v[2:3], 0, v[0:1]
	s_movk_i32 s0, 0x2000
	v_add_f32_e32 v0, v8, v18
	v_sub_f32_e32 v8, v16, v9
	v_add_co_u32_e32 v4, vcc, s0, v2
	v_add_f32_e32 v0, v8, v0
	s_nop 0
	v_addc_co_u32_e32 v5, vcc, 0, v3, vcc
	v_add_f32_e32 v16, v17, v0
	global_load_dwordx2 v[6:7], v[4:5], off offset:-4096
	global_load_dwordx2 v[8:9], v[4:5], off
	v_mul_f32_e32 v18, v14, v16
	v_mul_f32_e32 v4, v12, v18
	v_fma_f32 v5, v18, v12, -v4
	v_fmac_f32_e32 v5, v18, v13
	v_sub_f32_e32 v12, v17, v16
	v_add_f32_e32 v0, v0, v12
	v_add_f32_e32 v12, v4, v5
	v_sub_f32_e32 v17, v16, v12
	s_movk_i32 s0, 0x3000
	v_sub_f32_e32 v13, v16, v17
	v_add_co_u32_e32 v2, vcc, s0, v2
	v_sub_f32_e32 v4, v12, v4
	v_sub_f32_e32 v12, v13, v12
	v_addc_co_u32_e32 v3, vcc, 0, v3, vcc
	v_add_f32_e32 v0, v0, v12
	global_load_dwordx2 v[12:13], v[2:3], off
	s_lshl_b32 s20, s9, 10
	s_add_u32 s20, s34, s20
	s_addc_u32 s21, s35, 0
	v_lshlrev_b32_e32 v232, 4, v139
	global_load_dwordx4 v[226:229], v232, s[20:21]
	s_mov_b64 s[20:21], 0x1000
	v_lshl_add_u64 v[232:233], v[2:3], 0, s[20:21]
	global_load_dwordx2 v[230:231], v[232:233], off
	s_ashr_i32 s12, s38, 3
	s_ashr_i32 s13, s12, 31
	s_lshl_b64 s[12:13], s[12:13], 3
	s_add_u32 s12, s12, s26
	s_addc_u32 s13, s13, s27
	s_or_b32 s12, s12, s9
	s_lshl_b64 s[12:13], s[12:13], 18
	s_add_u32 s12, s50, s12
	s_addc_u32 s13, s51, s13
	v_lshlrev_b32_e32 v102, 4, v139
	v_lshl_add_u32 v102, v138, 15, v102
	s_add_u32 s14, s12, 0x1000
	s_addc_u32 s15, s13, 0
	s_add_u32 s16, s12, 0x2000
	s_addc_u32 s17, s13, 0
	s_add_u32 s18, s12, 0x3000
	s_addc_u32 s19, s13, 0
	global_load_dwordx4 v[86:89], v102, s[12:13] nt
	global_load_dwordx4 v[78:81], v102, s[12:13] offset:1024 nt
	global_load_dwordx4 v[74:77], v102, s[12:13] offset:2048 nt
	global_load_dwordx4 v[62:65], v102, s[12:13] offset:3072 nt
	global_load_dwordx4 v[54:57], v102, s[14:15] nt
	global_load_dwordx4 v[38:41], v102, s[14:15] offset:1024 nt
	global_load_dwordx4 v[46:49], v102, s[14:15] offset:2048 nt
	global_load_dwordx4 v[98:101], v102, s[14:15] offset:3072 nt
	global_load_dwordx4 v[90:93], v102, s[16:17] nt
	global_load_dwordx4 v[82:85], v102, s[16:17] offset:1024 nt
	global_load_dwordx4 v[70:73], v102, s[16:17] offset:2048 nt
	global_load_dwordx4 v[66:69], v102, s[16:17] offset:3072 nt
	global_load_dwordx4 v[58:61], v102, s[18:19] nt
	global_load_dwordx4 v[50:53], v102, s[18:19] offset:1024 nt
	global_load_dwordx4 v[42:45], v102, s[18:19] offset:2048 nt
	global_load_dwordx4 v[34:37], v102, s[18:19] offset:3072 nt
	v_sub_f32_e32 v2, v4, v5
	v_cvt_f32_i32_e32 v4, v11
	v_add_f32_e32 v0, v2, v0
	v_add_f32_e32 v2, v15, v18
	v_add_f32_e32 v0, v17, v0
	v_sub_f32_e32 v3, v2, v15
	v_mul_f32_e32 v0, v14, v0
	v_sub_f32_e32 v3, v18, v3
	v_add_f32_e32 v0, v3, v0
	v_mul_f32_e32 v14, 0x3f317218, v4
	s_mov_b32 s0, 0x3f317218
	v_add_f32_e32 v3, v2, v0
	v_fma_f32 v15, v4, s0, -v14
	v_mul_f32_e32 v5, v3, v3
	v_fmac_f32_e32 v15, 0xb102e308, v4
	v_sub_f32_e32 v2, v3, v2
	v_fmamk_f32 v11, v5, 0x3e9b6dac, v234
	v_sub_f32_e32 v0, v0, v2
	v_add_f32_e32 v2, v14, v15
	v_fmaak_f32 v11, v5, v11, 0x3f2aaada
	v_sub_f32_e32 v4, v2, v14
	v_ldexp_f32 v14, v3, 1
	v_mul_f32_e32 v3, v3, v5
	v_mul_f32_e32 v3, v3, v11
	v_add_f32_e32 v5, v14, v3
	v_sub_f32_e32 v11, v5, v14
	v_ldexp_f32 v0, v0, 1
	v_sub_f32_e32 v3, v3, v11
	v_add_f32_e32 v0, v0, v3
	v_add_f32_e32 v3, v5, v0
	v_sub_f32_e32 v5, v3, v5
	v_sub_f32_e32 v0, v0, v5
	v_add_f32_e32 v5, v2, v3
	v_sub_f32_e32 v11, v5, v2
	v_sub_f32_e32 v14, v5, v11
	v_sub_f32_e32 v4, v15, v4
	v_sub_f32_e32 v2, v2, v14
	v_sub_f32_e32 v3, v3, v11
	v_add_f32_e32 v2, v3, v2
	v_add_f32_e32 v3, v4, v0
	v_sub_f32_e32 v11, v3, v4
	v_sub_f32_e32 v14, v3, v11
	v_add_f32_e32 v2, v3, v2
	v_sub_f32_e32 v4, v4, v14
	v_sub_f32_e32 v0, v0, v11
	v_add_f32_e32 v3, v5, v2
	v_add_f32_e32 v0, v0, v4
	v_sub_f32_e32 v4, v3, v5
	v_sub_f32_e32 v2, v2, v4
	v_add_f32_e32 v0, v0, v2
	v_add_f32_e32 v0, v3, v0
	v_cmp_nlt_f32_e32 vcc, 1.0, v10
	s_mov_b32 s0, 0x33800000
	v_lshl_add_u32 v14, v138, 10, 0
	v_cndmask_b32_e32 v0, v238, v0, vcc
	v_cmp_neq_f32_e32 vcc, 1.0, v10
	v_lshlrev_b32_e32 v15, 4, v139
	v_add_u32_e32 v16, v14, v15
	v_cndmask_b32_e32 v0, v239, v0, vcc
	v_cmp_gt_f32_e32 vcc, s0, v10
	s_waitcnt vmcnt(18)
; #define LAS __attribute__((address_space(3)))
; __device__ __forceinline__ float bf_lo(unsigned u) { return __uint_as_float(u << 16); }
; __device__ __forceinline__ float bf_hi(unsigned u) { return __uint_as_float(u & 0xffff0000u); }
; __device__ void sample_ret_unit(const Params& p, int l, int unit, LAS unsigned char* lds, const int tid_in) {
;     ...
;     { const int i = tid >> 6, d = (tid & 63) * 4; const bf16_t* zr = zb + (size_t)(r0 + i) * ZW + h * 256 + d;
;         const u32x2 a = *(const u32x2*)(zr + ZC_Q), kk = *(const u32x2*)(zr + ZC_K), vv = *(const u32x2*)(zr + ZC_V);
;         const float qf[4] = {bf_lo(a.x), bf_hi(a.x), bf_lo(a.y), bf_hi(a.y)}, kf[4] = {bf_lo(kk.x), bf_hi(kk.x), bf_lo(kk.y), bf_hi(kk.y)};
;         const float dk = exp2f(lg * (float)(7 - i));
;         *(LAS f32x4*)(sq + i * 256 + d) = (f32x4){qf[0], qf[1], qf[2], qf[3]};
;         *(LAS f32x4*)(sk + i * 256 + d) = (f32x4){kf[0], kf[1], kf[2], kf[3]};
;         *(LAS f32x4*)(sv + i * 256 + d) = (f32x4){bf_lo(vv.x), bf_hi(vv.x), bf_lo(vv.y), bf_hi(vv.y)};
; #pragma unroll
;         for (int j = 0; j < 4; ++j) { sqT[(d + j) * 8 + i] = qf[j]; skdT[(d + j) * 8 + i] = kf[j] * dk; } }
;     __syncthreads();
;     { const int i = wid; const f32x4 qv = *(const LAS f32x4*)(sq + i * 256 + lane * 4);
;         for (int j = 0; j < 8; ++j) { const f32x4 kv = *(const LAS f32x4*)(sk + j * 256 + lane * 4);
;             float s = wave_sum(qv[0] * kv[0] + qv[1] * kv[1] + qv[2] * kv[2] + qv[3] * kv[3]);
;             if (lane == 0) sc[i * 8 + j] = j <= i ? s * exp2f(lg * (float)(i - j)) : 0.f; } }
	v_lshlrev_b32_e32 v2, 16, v6
	v_and_b32_e32 v3, 0xffff0000, v6
	v_cndmask_b32_e64 v0, v0, -v10, vcc
	v_mul_f32_e32 v145, 0x3fb8aa3b, v0
	v_sub_u32_e32 v0, 7, v138
	v_cvt_f32_i32_e32 v0, v0
	v_lshlrev_b32_e32 v4, 16, v7
	v_and_b32_e32 v5, 0xffff0000, v7
	v_lshlrev_b32_e32 v6, 16, v8
	v_and_b32_e32 v7, 0xffff0000, v8
	v_mul_f32_e32 v8, v145, v0
	v_cmp_gt_f32_e32 vcc, s75, v8
	v_add_u32_e32 v18, 0, v15
	s_movk_i32 s0, 0xfc20
	v_cndmask_b32_e32 v8, 0, v237, vcc
	v_fmac_f32_e32 v8, v145, v0
	v_exp_f32_e32 v0, v8
	v_cndmask_b32_e32 v10, 0, v240, vcc
	v_lshlrev_b32_e32 v8, 16, v9
	v_and_b32_e32 v11, 0xffff0000, v12
	v_ldexp_f32 v0, v0, v10
	v_lshlrev_b32_e32 v10, 16, v12
	v_lshlrev_b32_e32 v12, 16, v13
	v_and_b32_e32 v13, 0xffff0000, v13
	v_and_b32_e32 v9, 0xffff0000, v9
	ds_write_b128 v16, v[2:5]
	ds_write_b128 v16, v[6:9] offset:8192
	ds_write_b128 v16, v[10:13] offset:16384
	v_lshl_add_u32 v10, v139, 5, v138
	v_lshl_add_u32 v10, v10, 2, 0
	v_add_u32_e32 v11, 0x6000, v10
	v_mul_f32_e32 v6, v0, v6
	ds_write2_b32 v11, v2, v3 offset1:8
	v_mul_f32_e32 v2, v0, v7
	v_add_u32_e32 v3, 0x8000, v10
	ds_write2_b32 v3, v6, v2 offset1:8
	v_mul_f32_e32 v2, v0, v8
	v_mul_f32_e32 v0, v0, v9
	ds_write2_b32 v11, v4, v5 offset0:16 offset1:24
	ds_write2_b32 v3, v2, v0 offset0:16 offset1:24
	s_waitcnt lgkmcnt(0)
	s_barrier
	ds_read_b128 v[2:5], v16
	ds_read_b128 v[6:9], v18 offset:8192
	v_mul_lo_u32 v0, v138, s0
	v_cmp_eq_u32_e32 vcc, 0, v139
	v_add_u32_e32 v0, v14, v0
	s_waitcnt lgkmcnt(0)
	v_mul_f32_e32 v7, v3, v7
	v_fmac_f32_e32 v7, v2, v6
	v_fmac_f32_e32 v7, v4, v8
	v_fmac_f32_e32 v7, v5, v9
	s_nop 1
	v_add_f32_dpp v6, v7, v7 quad_perm:[1,0,3,2] row_mask:0xf bank_mask:0xf bound_ctrl:1
	s_nop 1
	v_add_f32_dpp v6, v6, v6 quad_perm:[2,3,0,1] row_mask:0xf bank_mask:0xf bound_ctrl:1
	s_nop 1
	v_add_f32_dpp v6, v6, v6 row_half_mirror row_mask:0xf bank_mask:0xf bound_ctrl:1
	s_nop 1
	v_add_f32_dpp v6, v6, v6 row_mirror row_mask:0xf bank_mask:0xf bound_ctrl:1
	s_nop 0
	v_readlane_b32 s6, v6, 0
	v_readlane_b32 s10, v6, 16
	v_readlane_b32 s7, v6, 32
	v_readlane_b32 s11, v6, 48
	s_and_saveexec_b64 s[0:1], vcc
	s_cbranch_execz .LBB0_525
	v_mov_b32_e32 v6, s10
	v_mov_b32_e32 v7, s11
	v_pk_add_f32 v[6:7], s[6:7], v[6:7]
	s_nop 0
	v_add_f32_e32 v6, v6, v7
	v_cvt_f32_i32_e32 v7, v138
	v_mul_f32_e32 v8, v145, v7
	v_cmp_gt_f32_e64 s[6:7], s75, v8
	s_nop 1
	v_cndmask_b32_e64 v9, 0, v237, s[6:7]
	v_fmac_f32_e32 v9, v145, v7
	v_exp_f32_e32 v7, v9
	v_cndmask_b32_e64 v8, 0, v240, s[6:7]
	v_cmp_lt_i32_e64 s[6:7], -1, v138
	v_ldexp_f32 v7, v7, v8
	v_mul_f32_e32 v6, v7, v6
	v_cndmask_b32_e64 v6, 0, v6, s[6:7]
	ds_write_b32 v0, v6 offset:40960
